# baseline (speedup 1.0000x reference)
; __device__ __forceinline__ unsigned xb_ld(unsigned* p)              { return __hip_atomic_load(p, __ATOMIC_RELAXED, __HIP_MEMORY_SCOPE_AGENT); }
; __device__ __forceinline__ unsigned xb_add(unsigned* p, unsigned v) { return __hip_atomic_fetch_add(p, v, __ATOMIC_RELAXED, __HIP_MEMORY_SCOPE_AGENT); }
; #define XB_SPIN(cond, bar) do { unsigned _sp = 0; while (cond) { __builtin_amdgcn_s_sleep(1); \
;     if ((++_sp & 255u) == 0u) { if (xb_ld(&(bar)[XB_TMO])) break; if (_sp > XB_SPIN_CAP) { atomicAdd(&(bar)[XB_TMO], 1u); break; } } } } while (0)
; __device__ __forceinline__ void xcd_barrier(const XcdBarrier& b) {
;     ...
;         const unsigned old = xb_add(&bar[XB_XSUB(b.x)], 1u);
;         const unsigned gen = old / nloc;
;         if (old + 1u == (gen + 1u) * nloc) {
;             __builtin_amdgcn_fence(__ATOMIC_RELEASE, "agent");
;             asm volatile("s_waitcnt vmcnt(0)" ::: "memory");
;             const unsigned og = xb_add(&bar[XB_TOP], 1u);
;             const unsigned tg = og / nx;
;             if (og + 1u == (tg + 1u) * nx) xb_add(&bar[XB_TOPGEN], 1u);
;             else XB_SPIN(xb_ld(&bar[XB_TOPGEN]) == tg, bar);
;             __builtin_amdgcn_fence(__ATOMIC_ACQUIRE, "agent");
;             xb_add(&bar[XB_XGEN(b.x)], 1u);
;             asm volatile("s_waitcnt vmcnt(0)" ::: "memory");
;         } else {
;             XB_SPIN(xb_ld(&bar[XB_XGEN(b.x)]) == gen, bar);
;             __builtin_amdgcn_fence(__ATOMIC_ACQUIRE, "agent");
;             asm volatile("s_waitcnt vmcnt(0)" ::: "memory");
;         }
.LBB0_653:
	v_readlane_b32 s0, v254, 32
	v_readlane_b32 s1, v254, 33
	v_mov_b32_e32 v1, 1
	v_sub_u32_e32 v4, 0, v2
	s_nop 2
	global_atomic_add v3, v149, v1, s[0:1] sc0
	v_cvt_f32_u32_e32 v1, v2
	v_rcp_iflag_f32_e32 v1, v1
	s_nop 0
	v_mul_f32_e32 v1, 0x4f7ffffe, v1
	v_cvt_u32_f32_e32 v1, v1
	v_mul_lo_u32 v4, v4, v1
	v_mul_hi_u32 v4, v1, v4
	v_add_u32_e32 v1, v1, v4
	s_waitcnt vmcnt(0)
	v_mul_hi_u32 v1, v3, v1
	v_mul_lo_u32 v4, v1, v2
	v_sub_u32_e32 v4, v3, v4
	v_add_u32_e32 v5, 1, v1
	v_cmp_ge_u32_e32 vcc, v4, v2
	v_add_u32_e32 v3, 1, v3
	s_nop 0
	v_cndmask_b32_e32 v1, v1, v5, vcc
	v_sub_u32_e32 v5, v4, v2
	v_cndmask_b32_e32 v4, v4, v5, vcc
	v_add_u32_e32 v5, 1, v1
	v_cmp_ge_u32_e32 vcc, v4, v2
	s_nop 1
	v_cndmask_b32_e32 v1, v1, v5, vcc
	v_mul_lo_u32 v4, v2, v1
	v_add_u32_e32 v2, v4, v2
	v_cmp_ne_u32_e32 vcc, v3, v2
	s_and_saveexec_b64 s[16:17], vcc
	s_xor_b64 s[16:17], exec, s[16:17]
	s_cbranch_execz .LBB0_667
	v_readlane_b32 s0, v254, 38
	v_readlane_b32 s1, v254, 39
	s_waitcnt lgkmcnt(0)
	s_nop 3
	global_load_dword v0, v149, s[0:1] sc1
	s_waitcnt vmcnt(0)
	v_cmp_eq_u32_e32 vcc, v0, v1
	s_and_saveexec_b64 s[18:19], vcc
	s_cbranch_execz .LBB0_666
	s_mov_b32 s5, 1
	s_mov_b64 s[20:21], 0
	s_branch .LBB0_657

; __device__ __forceinline__ unsigned xb_ld(unsigned* p)              { return __hip_atomic_load(p, __ATOMIC_RELAXED, __HIP_MEMORY_SCOPE_AGENT); }
; #define XB_SPIN(cond, bar) do { unsigned _sp = 0; while (cond) { __builtin_amdgcn_s_sleep(1); \
;     if ((++_sp & 255u) == 0u) { if (xb_ld(&(bar)[XB_TMO])) break; if (_sp > XB_SPIN_CAP) { atomicAdd(&(bar)[XB_TMO], 1u); break; } } } } while (0)
; __device__ __forceinline__ void xcd_barrier(const XcdBarrier& b) {
;     ...
;         } else {
;             XB_SPIN(xb_ld(&bar[XB_XGEN(b.x)]) == gen, bar);
;             __builtin_amdgcn_fence(__ATOMIC_ACQUIRE, "agent");
.LBB0_659:
	v_readlane_b32 s0, v254, 38
	v_readlane_b32 s1, v254, 39
	s_add_i32 s5, s5, 1
	s_mov_b64 s[40:41], -1
	s_nop 2
	global_load_dword v0, v149, s[0:1] sc1
	s_waitcnt vmcnt(0)
	v_cmp_ne_u32_e32 vcc, v0, v1
	s_orn2_b64 s[24:25], vcc, exec
	s_branch .LBB0_656
